# v19 plus all row-statistics loads of the score and up-projection epilogues issued together (one exposed memory round trip instead of two)
# speedup vs baseline: 1.0039x; 1.0039x over previous
; __device__ __forceinline__ float shx(float v, int mask, int lane) { return __int_as_float(__builtin_amdgcn_ds_bpermute((lane ^ mask) << 2, __float_as_int(v))); }
;     __device__ __forceinline__ void operator()(EPI_ARGS) const {
;     ...
;             for (int m = 0; m < 4; ++m) { const float rs = scale * __builtin_amdgcn_rsqf(ss[u.row0 + ai * HALF + wr * 64 + m * 16 + fr] * (1.f / D) + RMS_EPS);
; #pragma unroll
;                 for (int bj = 0; bj < 2; ++bj) { acc[ai][bj][m][0] = acc[ai][bj][m][0] * rs; acc[ai][bj][m][1] = acc[ai][bj][m][1] * rs; } }
;         float mw[2][4];
; #pragma unroll
;         for (int ai = 0; ai < 2; ++ai)
; #pragma unroll
;             for (int m = 0; m < 4; ++m) {
;                 float mx = -3.0e38f;
; #pragma unroll
;                 for (int bj = 0; bj < 2; ++bj)
; #pragma unroll
;                     for (int n = 0; n < 2; ++n) { const f32x4 x = acc[ai][bj][m][n]; mx = fmaxf(mx, fmaxf(fmaxf(x[0], x[1]), fmaxf(x[2], x[3]))); }
;                 mx = fmaxf(mx, shx(mx, 16, fq * 16 + fr)); mx = fmaxf(mx, shx(mx, 32, fq * 16 + fr));
;                 float s = 0.f;
; #pragma unroll
;                 for (int bj = 0; bj < 2; ++bj)
; #pragma unroll
;                     for (int n = 0; n < 2; ++n) { f32x4 x = acc[ai][bj][m][n];
; #pragma unroll
;                         for (int e = 0; e < 4; ++e) { x[e] = __builtin_amdgcn_exp2f(x[e] - mx); s += x[e]; } acc[ai][bj][m][n] = x; }
;                 s += shx(s, 16, fq * 16 + fr); s += shx(s, 32, fq * 16 + fr);
;                 mw[ai][m] = mx;
;                 if (fq == 0) X[(ai * HALF + wr * 64 + m * 16 + fr) * 4 + wc] = (f32x2_t){mx, s};
.LBB0_999:
	s_mov_b32 s5, -1
	s_nop 0
	v_mbcnt_lo_u32_b32 v140, s5, 0
	v_mbcnt_hi_u32_b32 v143, s5, v140
	v_and_b32_e32 v155, 15, v143
	v_or_b32_e32 v168, s49, v155
	v_add_u32_e32 v140, s4, v168
	v_ashrrev_i32_e32 v141, 31, v140
	v_lshl_add_u64 v[144:145], v[140:141], 2, s[14:15]
	global_load_dword v142, v[144:145], off
	global_load_dword v154, v[144:145], off offset:64
	global_load_dword v157, v[144:145], off offset:128
	global_load_dword v156, v[144:145], off offset:192
	global_load_dword v176, v[144:145], off offset:512
	global_load_dword v175, v[144:145], off offset:576
	global_load_dword v174, v[144:145], off offset:640
	v_or_b32_e32 v172, 16, v168
	v_or_b32_e32 v171, 32, v168
	v_or_b32_e32 v170, 48, v168
	v_add_u32_e32 v169, 0x80, v168
	v_lshrrev_b32_e32 v173, 4, v143
	v_cmp_gt_u32_e32 vcc, 16, v143
	v_lshl_add_u32 v177, v143, 5, s53
	s_waitcnt vmcnt(6)
	v_fmamk_f32 v142, v142, 0x3a800000, v218
	v_rsq_f32_e32 v142, v142
	s_nop 0
	v_mul_f32_e32 v142, 0x3db8aa3b, v142
	v_pk_mul_f32 v[146:147], v[112:113], v[142:143] op_sel_hi:[1,0]
	v_add_u32_e32 v112, s4, v172
	v_ashrrev_i32_e32 v113, 31, v112
	v_lshl_add_u64 v[112:113], v[112:113], 2, s[14:15]
	v_add_u32_e32 v112, s4, v171
	v_ashrrev_i32_e32 v113, 31, v112
	v_lshl_add_u64 v[112:113], v[112:113], 2, s[14:15]
	v_add_u32_e32 v112, s4, v170
	v_ashrrev_i32_e32 v113, 31, v112
	v_lshl_add_u64 v[112:113], v[112:113], 2, s[14:15]
	v_add_u32_e32 v112, s4, v169
	v_pk_mul_f32 v[150:151], v[126:127], v[142:143] op_sel_hi:[1,0]
	v_pk_mul_f32 v[126:127], v[116:117], v[142:143] op_sel_hi:[1,0]
	v_ashrrev_i32_e32 v113, 31, v112
	v_add_u32_e32 v116, 0x90, v140
	v_pk_mul_f32 v[148:149], v[114:115], v[142:143] op_sel_hi:[1,0]
	v_lshl_add_u64 v[112:113], v[112:113], 2, s[14:15]
	v_ashrrev_i32_e32 v117, 31, v116
	v_add_u32_e32 v114, 0xa0, v140
	v_lshl_add_u64 v[112:113], v[116:117], 2, s[14:15]
	v_ashrrev_i32_e32 v115, 31, v114
	v_lshl_add_u64 v[112:113], v[114:115], 2, s[14:15]
	v_add_u32_e32 v112, 0xb0, v140
	v_ashrrev_i32_e32 v113, 31, v112
	v_pk_mul_f32 v[144:145], v[118:119], v[142:143] op_sel_hi:[1,0]
	v_lshl_add_u64 v[118:119], v[112:113], 2, s[14:15]
	global_load_dword v113, v[118:119], off
	v_pk_mul_f32 v[152:153], v[124:125], v[142:143] op_sel_hi:[1,0]
	v_pk_mul_f32 v[124:125], v[122:123], v[142:143] op_sel_hi:[1,0]
	v_lshlrev_b32_e32 v117, 6, v173
	v_lshlrev_b32_e32 v118, 2, v155
	s_movk_i32 s4, 0x80
	v_pk_mul_f32 v[122:123], v[120:121], v[142:143] op_sel_hi:[1,0]
	v_bitop3_b32 v115, v117, 64, v118 bitop3:0x36
	v_bitop3_b32 v117, v117, s4, v118 bitop3:0x36
	v_max_f32_e32 v118, v150, v151
	v_max_f32_e32 v119, v124, v125
	v_max3_f32 v118, v152, v153, v118
	v_max3_f32 v119, v122, v123, v119
	s_mov_b32 s4, 0xff61b1e6
	v_max3_f32 v118, v118, s4, v119
	v_max_f32_e32 v119, v144, v145
	v_max_f32_e32 v120, v148, v149
	v_max3_f32 v119, v126, v127, v119
	v_max3_f32 v120, v146, v147, v120
	v_max3_f32 v118, v118, v119, v120
	ds_bpermute_b32 v119, v115, v118
	s_waitcnt lgkmcnt(0)
	v_max_f32_e32 v119, v119, v119
	v_max_f32_e32 v118, v118, v119
	ds_bpermute_b32 v119, v117, v118
	s_waitcnt lgkmcnt(0)
	v_max_f32_e32 v119, v119, v119
	v_max_f32_e32 v142, v118, v119
	v_sub_f32_e32 v118, v152, v142
	v_exp_f32_e32 v118, v118
	v_sub_f32_e32 v119, v153, v142
	v_exp_f32_e32 v119, v119
	v_sub_f32_e32 v122, v122, v142
	v_add_f32_e32 v120, 0, v118
	v_exp_f32_e32 v122, v122
	v_add_f32_e32 v121, v119, v120
	v_sub_f32_e32 v120, v150, v142
	v_exp_f32_e32 v120, v120
	v_sub_f32_e32 v123, v123, v142
	v_exp_f32_e32 v123, v123
	v_sub_f32_e32 v124, v124, v142
	v_add_f32_e32 v150, v120, v121
	v_sub_f32_e32 v121, v151, v142
	v_exp_f32_e32 v121, v121
	v_exp_f32_e32 v124, v124
	v_sub_f32_e32 v125, v125, v142
	v_exp_f32_e32 v125, v125
	v_add_f32_e32 v150, v121, v150
	v_sub_f32_e32 v126, v126, v142
	v_add_f32_e32 v150, v122, v150
	v_exp_f32_e32 v126, v126
	v_sub_f32_e32 v127, v127, v142
	v_add_f32_e32 v150, v123, v150
	v_exp_f32_e32 v127, v127
	v_sub_f32_e32 v144, v144, v142
	v_add_f32_e32 v150, v124, v150
	v_exp_f32_e32 v144, v144
	v_sub_f32_e32 v145, v145, v142
	v_add_f32_e32 v150, v125, v150
	v_exp_f32_e32 v145, v145
	v_sub_f32_e32 v146, v146, v142
	v_add_f32_e32 v150, v126, v150
	v_exp_f32_e32 v146, v146
	v_sub_f32_e32 v147, v147, v142
	v_add_f32_e32 v150, v127, v150
	v_exp_f32_e32 v147, v147
	v_sub_f32_e32 v148, v148, v142
	v_add_f32_e32 v150, v144, v150
	v_exp_f32_e32 v148, v148
	v_sub_f32_e32 v149, v149, v142
	v_add_f32_e32 v150, v145, v150
	v_exp_f32_e32 v149, v149
	v_add_f32_e32 v150, v146, v150
	v_add_f32_e32 v150, v147, v150
	v_add_f32_e32 v150, v148, v150
	v_add_f32_e32 v150, v149, v150
	ds_bpermute_b32 v151, v115, v150
	s_waitcnt lgkmcnt(0)
	v_add_f32_e32 v150, v150, v151
	ds_bpermute_b32 v151, v117, v150
	s_and_saveexec_b64 s[4:5], vcc
	s_cbranch_execz .LBB0_1001
	s_waitcnt lgkmcnt(0)
	v_add_f32_e32 v143, v150, v151
	ds_write_b64 v177, v[142:143]

; #define LAS __attribute__((address_space(3)))
;     __device__ __forceinline__ void operator()(EPI_ARGS) const {
;     ...
;             for (int m = 0; m < 4; ++m) { const float rs = __builtin_amdgcn_rsqf(ss[u.row0 + ai * HALF + wr * 64 + m * 16 + fr] * (1.f / D) + RMS_EPS);
; #pragma unroll
;                 for (int bj = 0; bj < 2; ++bj) { acc[ai][bj][m][0] = acc[ai][bj][m][0] * rs; acc[ai][bj][m][1] = acc[ai][bj][m][1] * rs; } }
;         LAS float* X = (LAS float*)(lds + xoff);
;         const int pn = u.col0 >> 8, pm = u.row0 >> 8, cl = wc * 32 + 8 * fq, ch = pn * 128 + cl;
;         const bool samp = u.row0 >= MP;
;         if (fr >= 14) {
; #pragma unroll
;             for (int ai = 0; ai < 2; ++ai) {
; #pragma unroll
;                 for (int bj = 0; bj < 2; ++bj)
; #pragma unroll
;                     for (int n = 0; n < 2; ++n) *(LAS f32x4*)(X + ((ai * 2 + wr) * 2 + (fr - 14)) * 256 + bj * HALF + cl + 4 * n) = acc[ai][bj][3][n];
.LBB0_1393:
	s_mov_b32 s6, -1
	s_add_i32 s62, s9, s29
	v_mbcnt_lo_u32_b32 v140, s6, 0
	v_mbcnt_hi_u32_b32 v145, s6, v140
	v_and_b32_e32 v148, 15, v145
	v_add_u32_e32 v140, s62, v148
	v_ashrrev_i32_e32 v141, 31, v140
	v_lshl_add_u64 v[142:143], v[140:141], 2, s[46:47]
	global_load_dword v154, v[142:143], off
	global_load_dword v153, v[142:143], off offset:64
	global_load_dword v152, v[142:143], off offset:128
	global_load_dword v141, v[142:143], off offset:192
	global_load_dword v151, v[142:143], off offset:512
	global_load_dword v150, v[142:143], off offset:576
	global_load_dword v250, v[142:143], off offset:640
	global_load_dword v251, v[142:143], off offset:704
	s_ashr_i32 s6, s8, 1
	s_ashr_i32 s10, s9, 8
	s_and_b32 s6, s6, 0xffffff80
	s_cmp_lt_i32 s9, 0x10000
	s_cselect_b64 s[14:15], -1, 0
	s_cmp_gt_i32 s9, 0xffff
	s_cselect_b64 s[48:49], -1, 0
	v_cmp_lt_u32_e32 vcc, 13, v148
	s_waitcnt vmcnt(4)
	v_fmamk_f32 v141, v141, 0x3a800000, v218
	v_rsq_f32_e32 v144, v141
	s_nop 0
	v_pk_mul_f32 v[126:127], v[126:127], v[144:145] op_sel_hi:[1,0]
	v_pk_mul_f32 v[124:125], v[124:125], v[144:145] op_sel_hi:[1,0]
	v_pk_mul_f32 v[122:123], v[122:123], v[144:145] op_sel_hi:[1,0]
	v_pk_mul_f32 v[120:121], v[120:121], v[144:145] op_sel_hi:[1,0]
	v_pk_mul_f32 v[118:119], v[118:119], v[144:145] op_sel_hi:[1,0]
	v_pk_mul_f32 v[116:117], v[116:117], v[144:145] op_sel_hi:[1,0]
	v_pk_mul_f32 v[114:115], v[114:115], v[144:145] op_sel_hi:[1,0]
	v_pk_mul_f32 v[112:113], v[112:113], v[144:145] op_sel_hi:[1,0]
	s_waitcnt vmcnt(0)
	v_mov_b32_e32 v141, v250
	v_fmamk_f32 v142, v251, 0x3a800000, v218
	v_rsq_f32_e32 v142, v142
	s_nop 0
	v_pk_mul_f32 v[110:111], v[110:111], v[142:143] op_sel_hi:[1,0]
	v_pk_mul_f32 v[108:109], v[108:109], v[142:143] op_sel_hi:[1,0]
	v_pk_mul_f32 v[106:107], v[106:107], v[142:143] op_sel_hi:[1,0]
	v_pk_mul_f32 v[104:105], v[104:105], v[142:143] op_sel_hi:[1,0]
	v_pk_mul_f32 v[102:103], v[102:103], v[142:143] op_sel_hi:[1,0]
	v_pk_mul_f32 v[100:101], v[100:101], v[142:143] op_sel_hi:[1,0]
	v_pk_mul_f32 v[98:99], v[98:99], v[142:143] op_sel_hi:[1,0]
	v_pk_mul_f32 v[96:97], v[96:97], v[142:143] op_sel_hi:[1,0]
	v_lshrrev_b32_e32 v142, 1, v145
	v_and_b32_e32 v142, 56, v142
	v_add_u32_e32 v149, s88, v142
	v_add_u32_e32 v142, s6, v149
	v_ashrrev_i32_e32 v143, 31, v142
	s_and_saveexec_b64 s[6:7], vcc
	s_cbranch_execz .LBB0_1405
	s_add_i32 s11, 0, 0x20000
	v_lshl_add_u32 v144, v149, 2, s11
	v_add_lshl_u32 v145, s65, v148, 10
	s_add_i32 s11, s62, 0xffff0000
	v_add_u32_e32 v196, -14, v148
	v_add_u32_e32 v144, v144, v145
	s_and_b64 vcc, exec, s[48:49]
	ds_write_b128 v144, v[124:127]
	ds_write_b128 v144, v[120:123] offset:16
	ds_write_b128 v144, v[116:119] offset:512
	ds_write_b128 v144, v[112:115] offset:528
	s_cbranch_vccz .LBB0_1396
	s_ashr_i32 s12, s11, 6
	s_ashr_i32 s13, s12, 31
	v_lshl_add_u64 v[156:157], s[12:13], 1, v[196:197]
	v_mov_b64_e32 v[158:159], s[30:31]
	s_movk_i32 s38, 0x5800
	v_mad_u64_u32 v[158:159], s[12:13], v156, s38, v[158:159]
	v_mad_i32_i24 v159, v157, s38, v159
	v_lshl_add_u64 v[156:157], v[142:143], 2, v[158:159]
	global_store_dwordx4 v[156:157], v[124:127], off
	global_store_dwordx4 v[156:157], v[120:123], off offset:16
	v_add_co_u32_e32 v156, vcc, 0x2000, v156
	s_nop 1
	v_addc_co_u32_e32 v157, vcc, 0, v157, vcc
	global_store_dwordx4 v[156:157], v[116:119], off offset:3072
	global_store_dwordx4 v[156:157], v[112:115], off offset:3088
